# layer-0 attention tile loop: all 4 K fragments and the 4 V^T fragments read from LDS early into free VGPRs (counted lgkmcnt waits) instead of just-in-time singles (on v103)
# baseline (speedup 1.0000x reference)
.LBB0_477:
	s_lshl_b32 s5, s5, 5
	s_sub_i32 s8, s5, 64
	v_add_u32_e32 v82, s8, v139
	v_add_u32_e32 v86, s8, v138
	v_add_u32_e32 v90, s8, v137
	v_add_u32_e32 v94, s8, v111
	s_ashr_i32 s9, s8, 31
	v_ashrrev_i32_e32 v83, 31, v82
	v_ashrrev_i32_e32 v87, 31, v86
	v_ashrrev_i32_e32 v91, 31, v90
	v_ashrrev_i32_e32 v95, 31, v94
	s_lshl_b64 s[16:17], s[8:9], 1
	v_lshlrev_b64 v[82:83], 13, v[82:83]
	v_lshlrev_b64 v[86:87], 13, v[86:87]
	v_lshlrev_b64 v[90:91], 13, v[90:91]
	v_lshlrev_b64 v[94:95], 13, v[94:95]
	v_lshl_add_u64 v[66:67], v[128:129], 0, s[16:17]
	v_lshl_add_u64 v[70:71], v[130:131], 0, s[16:17]
	v_lshl_add_u64 v[74:75], v[132:133], 0, s[16:17]
	v_lshl_add_u64 v[78:79], v[134:135], 0, s[16:17]
	v_lshl_add_u64 v[82:83], v[124:125], 0, v[82:83]
	v_lshl_add_u64 v[86:87], v[120:121], 0, v[86:87]
	v_lshl_add_u64 v[90:91], v[122:123], 0, v[90:91]
	v_lshl_add_u64 v[94:95], v[120:121], 0, v[94:95]
	global_load_dwordx4 v[66:69], v[66:67], off
	s_add_i32 s8, s46, -1
	global_load_dwordx4 v[70:73], v[70:71], off
	s_max_u32 s5, s8, 2
	global_load_dwordx4 v[74:77], v[74:75], off
	s_nop 0
	global_load_dwordx4 v[78:81], v[78:79], off
	s_nop 0
	global_load_dwordx4 v[82:85], v[82:83], off
	s_nop 0
	global_load_dwordx4 v[86:89], v[86:87], off
	s_nop 0
	global_load_dwordx4 v[90:93], v[90:91], off
	s_nop 0
	global_load_dwordx4 v[94:97], v[94:95], off
	s_waitcnt vmcnt(15)
	ds_write_b128 v140, v[34:37]
	s_waitcnt vmcnt(14)
	ds_write_b128 v140, v[38:41] offset:1024
	s_waitcnt vmcnt(13)
	ds_write_b128 v140, v[42:45] offset:2048
	s_waitcnt vmcnt(12)
	ds_write_b128 v140, v[46:49] offset:3072
	s_waitcnt vmcnt(11)
	ds_write_b128 v141, v[98:101] offset:4096
	s_waitcnt vmcnt(10)
	ds_write_b128 v141, v[102:105] offset:5120
	s_waitcnt vmcnt(9)
	ds_write_b128 v141, v[106:109] offset:6144
	s_waitcnt vmcnt(8)
	ds_write_b128 v141, v[116:119] offset:7168
	ds_read_b128 v[34:37], v144
	ds_read_b128 v[98:101], v145
	ds_read_b128 v[222:225], v146
	ds_read_b128 v[226:229], v147
	s_waitcnt lgkmcnt(3)
	v_mfma_f32_32x32x16_bf16 v[34:49], v[34:37], v[50:53], 0
	s_waitcnt lgkmcnt(2)
	v_mfma_f32_32x32x16_bf16 v[34:49], v[98:101], v[54:57], v[34:49]
	s_waitcnt lgkmcnt(1)
	v_mfma_f32_32x32x16_bf16 v[34:49], v[222:225], v[58:61], v[34:49]
	s_waitcnt lgkmcnt(0)
	v_mfma_f32_32x32x16_bf16 v[34:49], v[226:229], v[62:65], v[34:49]
	ds_read_b128 v[230:233], v143 offset:4096
	ds_read_b128 v[234:237], v136 offset:4096
	ds_read_b128 v[238:241], v143 offset:6144
	ds_read_b128 v[242:245], v136 offset:6144
	s_nop 11
	v_mul_f32_e32 v1, 0x3e38aa3b, v34
	v_exp_f32_e64 v34, -|v1|
	v_min_f32_e32 v98, 0, v1
	v_min_f32_e64 v1, -v1, 0
	v_add_f32_e32 v34, 1.0, v34
	v_log_f32_e32 v34, v34
	s_nop 0
	v_sub_f32_e32 v100, v98, v34
	v_sub_f32_e32 v1, v1, v34
	v_mul_f32_e32 v34, 0x3e38aa3b, v35
	v_exp_f32_e64 v35, -|v34|
	v_min_f32_e32 v98, 0, v34
	v_min_f32_e64 v34, -v34, 0
	v_add_f32_e32 v35, 1.0, v35
	v_log_f32_e32 v35, v35
	s_nop 0
	v_sub_f32_e32 v101, v98, v35
	v_sub_f32_e32 v34, v34, v35
	v_mul_f32_e32 v35, 0x3e38aa3b, v36
	v_exp_f32_e64 v36, -|v35|
	v_min_f32_e32 v98, 0, v35
	v_min_f32_e64 v35, -v35, 0
	v_add_f32_e32 v36, 1.0, v36
	v_log_f32_e32 v36, v36
	s_nop 0
	v_sub_f32_e32 v102, v98, v36
	v_sub_f32_e32 v35, v35, v36
	v_mul_f32_e32 v36, 0x3e38aa3b, v37
	v_exp_f32_e64 v37, -|v36|
	v_min_f32_e32 v98, 0, v36
	v_min_f32_e64 v36, -v36, 0
	v_add_f32_e32 v37, 1.0, v37
	v_log_f32_e32 v37, v37
	s_nop 0
	v_sub_f32_e32 v103, v98, v37
	v_sub_f32_e32 v36, v36, v37
	v_mul_f32_e32 v37, 0x3e38aa3b, v38
	v_exp_f32_e64 v38, -|v37|
	v_min_f32_e32 v98, 0, v37
	v_min_f32_e64 v37, -v37, 0
	v_add_f32_e32 v38, 1.0, v38
	v_log_f32_e32 v38, v38
	s_nop 0
	v_sub_f32_e32 v104, v98, v38
	v_sub_f32_e32 v37, v37, v38
	v_mul_f32_e32 v38, 0x3e38aa3b, v39
	v_exp_f32_e64 v39, -|v38|
	v_min_f32_e32 v98, 0, v38
	v_min_f32_e64 v38, -v38, 0
	v_add_f32_e32 v39, 1.0, v39
	v_log_f32_e32 v39, v39
	s_nop 0
	v_sub_f32_e32 v105, v98, v39
	v_sub_f32_e32 v38, v38, v39
	v_mul_f32_e32 v39, 0x3e38aa3b, v40
	v_exp_f32_e64 v40, -|v39|
	v_min_f32_e32 v98, 0, v39
	v_min_f32_e64 v39, -v39, 0
	v_add_f32_e32 v40, 1.0, v40
	v_log_f32_e32 v40, v40
	s_nop 0
	v_sub_f32_e32 v106, v98, v40
	v_sub_f32_e32 v39, v39, v40
	v_mul_f32_e32 v40, 0x3e38aa3b, v41
	v_exp_f32_e64 v41, -|v40|
	v_min_f32_e32 v98, 0, v40
	v_min_f32_e64 v40, -v40, 0
	v_add_f32_e32 v41, 1.0, v41
	v_log_f32_e32 v41, v41
	s_nop 0
	v_sub_f32_e32 v98, v98, v41
	v_sub_f32_e32 v40, v40, v41
	v_mul_f32_e32 v41, 0x3e38aa3b, v42
	v_exp_f32_e64 v42, -|v41|
	v_min_f32_e32 v99, 0, v41
	v_min_f32_e64 v41, -v41, 0
	v_add_f32_e32 v42, 1.0, v42
	v_log_f32_e32 v42, v42
	s_nop 0
	v_sub_f32_e32 v107, v99, v42
	v_sub_f32_e32 v41, v41, v42
	v_mul_f32_e32 v42, 0x3e38aa3b, v43
	v_exp_f32_e64 v43, -|v42|
	v_min_f32_e32 v99, 0, v42
	v_min_f32_e64 v42, -v42, 0
	v_add_f32_e32 v43, 1.0, v43
	v_log_f32_e32 v43, v43
	s_nop 0
	v_sub_f32_e32 v108, v99, v43
	v_sub_f32_e32 v42, v42, v43
	v_mul_f32_e32 v43, 0x3e38aa3b, v44
	v_exp_f32_e64 v44, -|v43|
	v_min_f32_e32 v99, 0, v43
	v_min_f32_e64 v43, -v43, 0
	v_add_f32_e32 v44, 1.0, v44
	v_log_f32_e32 v44, v44
	s_nop 0
	v_sub_f32_e32 v109, v99, v44
	v_sub_f32_e32 v43, v43, v44
	v_mul_f32_e32 v44, 0x3e38aa3b, v45
	v_exp_f32_e64 v45, -|v44|
	v_min_f32_e32 v99, 0, v44
	v_min_f32_e64 v44, -v44, 0
	v_add_f32_e32 v45, 1.0, v45
	v_log_f32_e32 v45, v45
	s_nop 0
	v_sub_f32_e32 v116, v99, v45
	v_sub_f32_e32 v44, v44, v45
	v_mul_f32_e32 v45, 0x3e38aa3b, v46
	v_exp_f32_e64 v46, -|v45|
	v_min_f32_e32 v99, 0, v45
	v_min_f32_e64 v45, -v45, 0
	v_add_f32_e32 v46, 1.0, v46
	v_log_f32_e32 v46, v46
	s_nop 0
	v_sub_f32_e32 v117, v99, v46
	v_sub_f32_e32 v45, v45, v46
	v_mul_f32_e32 v46, 0x3e38aa3b, v47
	v_exp_f32_e64 v47, -|v46|
	v_min_f32_e32 v99, 0, v46
	v_min_f32_e64 v46, -v46, 0
	v_add_f32_e32 v47, 1.0, v47
	v_log_f32_e32 v47, v47
	s_nop 0
	v_sub_f32_e32 v118, v99, v47
	v_sub_f32_e32 v46, v46, v47
	v_mul_f32_e32 v47, 0x3e38aa3b, v48
	v_exp_f32_e64 v48, -|v47|
	v_min_f32_e32 v99, 0, v47
	v_min_f32_e64 v47, -v47, 0
	v_add_f32_e32 v48, 1.0, v48
	v_log_f32_e32 v48, v48
	s_nop 0
	v_sub_f32_e32 v119, v99, v48
	v_sub_f32_e32 v47, v47, v48
	v_mul_f32_e32 v48, 0x3e38aa3b, v49
	v_exp_f32_e64 v99, -|v48|
	v_min_f32_e64 v49, -v48, 0
	v_min_f32_e32 v48, 0, v48
	v_add_f32_e32 v99, 1.0, v99
	v_log_f32_e32 v99, v99
	s_nop 0
	v_sub_f32_e32 v49, v49, v99
	v_sub_f32_e32 v127, v48, v99
	v_add_f32_e32 v48, 0, v40
	v_add_f32_e32 v49, 0, v49
	v_add_f32_e32 v39, v39, v48
	v_add_f32_e32 v47, v47, v49
	v_add_f32_e32 v148, v38, v39
	v_add_f32_e32 v46, v46, v47
	v_add_f32_e32 v149, v37, v148
	v_add_f32_e32 v45, v45, v46
	v_add_f32_e32 v150, v36, v149
	v_add_f32_e32 v44, v44, v45
	v_add_f32_e32 v151, v35, v150
	v_add_f32_e32 v43, v43, v44
	v_add_f32_e32 v40, v34, v151
	v_add_f32_e32 v42, v42, v43
	v_add_f32_e32 v35, v1, v40
	v_add_f32_e32 v37, v41, v42
	ds_bpermute_b32 v34, v142, v35
	ds_bpermute_b32 v36, v142, v37
	v_add_f32_e32 v1, v126, v37
	v_add_f32_e32 v100, v100, v40
	v_add_f32_e32 v40, v107, v42
	v_add_f32_e32 v41, v108, v43
	s_waitcnt lgkmcnt(0)
	v_add_f32_e32 v99, v1, v36
	v_cndmask_b32_e64 v1, 0, v34, s[40:41]
	v_add_f32_e32 v107, v102, v150
	v_add_f32_e32 v108, v103, v149
	v_add_f32_e32 v39, v105, v39
	v_pk_add_f32 v[102:103], v[0:1], v[98:99]
	v_add_f32_e32 v105, v106, v48
	v_add_f32_e32 v39, v39, v103
	v_exp_f32_e32 v99, v39
	v_add_f32_e32 v39, v105, v103
	v_add_f32_e32 v101, v101, v151
	v_add_f32_e32 v1, v100, v103
	v_exp_f32_e32 v100, v39
	v_add_f32_e32 v39, v102, v103
	v_cndmask_b32_e64 v38, 0, v36, s[40:41]
	v_add_f32_e32 v43, v116, v45
	v_add_f32_e32 v45, v118, v47
	v_add_f32_e32 v47, v101, v103
	v_exp_f32_e32 v101, v39
	v_mov_b32_e32 v39, v0
	v_pk_add_f32 v[38:39], v[126:127], v[38:39]
	v_add_f32_e32 v42, v109, v44
	v_add_f32_e32 v40, v38, v40
	v_add_f32_e32 v104, v104, v148
	v_exp_f32_e32 v102, v40
	v_add_f32_e32 v40, v38, v41
	v_add_f32_e32 v44, v117, v46
	v_add_f32_e32 v46, v119, v49
	v_add_f32_e32 v48, v107, v103
	v_add_f32_e32 v49, v108, v103
	v_add_f32_e32 v98, v104, v103
	v_exp_f32_e32 v103, v40
	v_add_f32_e32 v40, v38, v42
	v_exp_f32_e32 v104, v40
	v_add_f32_e32 v40, v38, v43
	v_exp_f32_e32 v43, v40
	v_add_f32_e32 v40, v38, v44
	v_exp_f32_e32 v44, v40
	v_add_f32_e32 v40, v38, v45
	v_exp_f32_e32 v45, v40
	v_add_f32_e32 v40, v38, v46
	v_add_f32_e32 v38, v38, v39
	v_exp_f32_e32 v1, v1
	v_exp_f32_e32 v47, v47
	v_exp_f32_e32 v48, v48
	v_exp_f32_e32 v49, v49
	v_exp_f32_e32 v46, v40
	v_exp_f32_e32 v105, v38
	v_cvt_pk_bf16_f32 v38, v1, v47
	v_cvt_pk_bf16_f32 v39, v48, v49
	v_cvt_pk_bf16_f32 v44, v44, v45
	v_cvt_pk_bf16_f32 v45, v46, v105
	v_exp_f32_e32 v98, v98
	v_cvt_pk_bf16_f32 v41, v100, v101
	v_cvt_pk_bf16_f32 v42, v102, v103
	v_cvt_pk_bf16_f32 v43, v104, v43
	v_cvt_pk_bf16_f32 v40, v98, v99
	v_pk_add_f32 v[34:35], v[34:35], v[36:37]
	s_waitcnt lgkmcnt(0)
	v_mfma_f32_32x32x16_bf16 v[2:17], v[230:233], v[38:41], v[2:17]
	v_add_f32_e32 v1, v34, v35
	v_add_f32_e32 v126, v126, v1
	v_cmp_gt_f32_e32 vcc, s53, v126
	s_cmp_lg_u64 vcc, exec
	s_cselect_b64 s[16:17], -1, 0
	s_cmp_gt_u32 s46, 1
	s_waitcnt lgkmcnt(0)
	v_mfma_f32_32x32x16_bf16 v[2:17], v[234:237], v[42:45], v[2:17]
	s_cselect_b64 s[42:43], -1, 0
	s_and_b64 s[16:17], s[16:17], s[42:43]
	s_waitcnt lgkmcnt(0)
	v_mfma_f32_32x32x16_bf16 v[18:33], v[238:241], v[38:41], v[18:33]
	s_and_b64 vcc, exec, s[16:17]
	s_mov_b32 s46, s8
	s_waitcnt lgkmcnt(0)
	v_mfma_f32_32x32x16_bf16 v[18:33], v[242:245], v[42:45], v[18:33]
	s_waitcnt vmcnt(0)
	v_mov_b64_e32 v[100:101], v[80:81]
	v_mov_b64_e32 v[34:35], v[94:95]
	v_mov_b64_e32 v[104:105], v[76:77]
	v_mov_b64_e32 v[108:109], v[72:73]
	v_mov_b64_e32 v[118:119], v[68:69]
	v_mov_b64_e32 v[46:47], v[82:83]
	v_mov_b64_e32 v[36:37], v[96:97]
	v_mov_b64_e32 v[48:49], v[84:85]
	v_mov_b64_e32 v[98:99], v[78:79]
	v_mov_b64_e32 v[38:39], v[90:91]
	v_mov_b64_e32 v[42:43], v[86:87]
	v_mov_b64_e32 v[40:41], v[92:93]
	v_mov_b64_e32 v[44:45], v[88:89]
	v_mov_b64_e32 v[102:103], v[74:75]
	v_mov_b64_e32 v[106:107], v[70:71]
	v_mov_b64_e32 v[116:117], v[66:67]
	s_cbranch_vccnz .LBB0_477
